# adds: branch GEMM mid-K gate rescale waits per gate quad (counted vmcnt) so the rescale arithmetic overlaps the remaining gate loads
# speedup vs baseline: 1.0087x; 1.0064x over previous
; #define GAS __attribute__((address_space(1)))
;     __device__ __forceinline__ void mid(f32x4 (&acc)[2][2][4][2], const pg8::GUnit& u, int b, int wr, int wc, int fr, int fq) const {
;     ...
;         const GAS unsigned char* gp = (const GAS unsigned char*)P + (size_t)(u.pm * 256 + (wr * 4 + wc) * 32 + fq) * (INW * 2) + (GA * 2 + (b * 16 + u.pn) * 256 + fr * 16);
;         u32x4 gn[8], gd[8];
; #pragma unroll
;         for (int k = 0; k < 8; ++k) { const GAS unsigned char* q = gp + (size_t)(k * 4) * (INW * 2); gn[k] = *(const GAS u32x4*)q; gd[k] = *(const GAS u32x4*)(q + DM); }
; #pragma unroll
;         for (int k = 0; k < 8; ++k) { const int ai = k >> 2, m = k & 3;
;             gate_ratio4(acc[ai][0][m][0], gn[k].x, gd[k].x); gate_ratio4(acc[ai][0][m][1], gn[k].y, gd[k].y); gate_ratio4(acc[ai][1][m][0], gn[k].z, gd[k].z); gate_ratio4(acc[ai][1][m][1], gn[k].w, gd[k].w); }
.Lbr_mid1_load:
	s_cmpk_eq_i32 s89, 0xc00
	v_ashrrev_i32_e32 v2, 4, v0
	v_add_u32_e32 v2, s84, v2
	v_mad_i64_i32 v[2:3], s[8:9], v2, s93, v[200:201]
	s_cselect_b32 s8, 0, 0x1000
	v_lshlrev_b32_e32 v0, 4, v0
	s_add_i32 s8, s87, s8
	v_and_b32_e32 v0, 0xf0, v0
	v_or_b32_e32 v132, s8, v0
	v_ashrrev_i32_e32 v133, 31, v132
	v_lshl_add_u64 v[2:3], v[2:3], 0, v[132:133]
	v_add_co_u32_e32 v132, vcc, s35, v2
	s_nop 0
	v_addc_co_u32_e32 v133, vcc, 0, v3, vcc
	global_load_dwordx4 v[192:195], v[132:133], off
	s_mov_b32 s8, 0x31000
	v_add_co_u32_e32 v132, vcc, s8, v2
	s_mov_b32 s8, 0x61000
	s_nop 0
	v_addc_co_u32_e32 v133, vcc, 0, v3, vcc
	global_load_dwordx4 v[184:187], v[132:133], off
	v_add_co_u32_e32 v132, vcc, s8, v2
	s_mov_b32 s8, 0x91000
	s_nop 0
	v_addc_co_u32_e32 v133, vcc, 0, v3, vcc
	global_load_dwordx4 v[176:179], v[132:133], off
	v_add_co_u32_e32 v132, vcc, s8, v2
	s_mov_b32 s8, 0xc1000
	s_nop 0
	v_addc_co_u32_e32 v133, vcc, 0, v3, vcc
	global_load_dwordx4 v[168:171], v[132:133], off
	v_add_co_u32_e32 v132, vcc, s8, v2
	s_mov_b32 s8, 0xf1000
	s_nop 0
	v_addc_co_u32_e32 v133, vcc, 0, v3, vcc
	global_load_dwordx4 v[160:163], v[132:133], off
	v_add_co_u32_e32 v132, vcc, s8, v2
	s_mov_b32 s8, 0x121000
	s_nop 0
	v_addc_co_u32_e32 v133, vcc, 0, v3, vcc
	global_load_dwordx4 v[152:155], v[132:133], off
	v_add_co_u32_e32 v132, vcc, s8, v2
	s_mov_b32 s8, 0x151000
	s_nop 0
	v_addc_co_u32_e32 v133, vcc, 0, v3, vcc
	v_add_co_u32_e32 v2, vcc, s8, v2
	global_load_dwordx4 v[144:147], v[132:133], off
	v_addc_co_u32_e32 v3, vcc, 0, v3, vcc
	global_load_dwordx4 v[136:139], v[2:3], off
	v_mov_b32_e32 v188, v215
	v_mov_b32_e32 v189, v216
	v_mov_b32_e32 v190, v217
	v_mov_b32_e32 v191, v218
	v_mov_b32_e32 v180, v219
	v_mov_b32_e32 v181, v220
	v_mov_b32_e32 v182, v221
	v_mov_b32_e32 v183, v222
	v_mov_b32_e32 v172, v223
	v_mov_b32_e32 v173, v224
	v_mov_b32_e32 v174, v225
	v_mov_b32_e32 v175, v226
	v_mov_b32_e32 v164, v227
	v_mov_b32_e32 v165, v228
	v_mov_b32_e32 v166, v229
	v_mov_b32_e32 v167, v230
	v_mov_b32_e32 v156, v231
	v_mov_b32_e32 v157, v232
	v_mov_b32_e32 v158, v233
	v_mov_b32_e32 v159, v234
	v_mov_b32_e32 v148, v235
	v_mov_b32_e32 v149, v236
	v_mov_b32_e32 v150, v237
	v_mov_b32_e32 v151, v238
	v_mov_b32_e32 v140, v239
	v_mov_b32_e32 v141, v240
	v_mov_b32_e32 v142, v241
	v_mov_b32_e32 v143, v242
	v_mov_b32_e32 v132, v243
	v_mov_b32_e32 v133, v245
	v_mov_b32_e32 v134, v246
	v_mov_b32_e32 v135, v247
	s_waitcnt vmcnt(7)
	v_mov_b32_e32 v215, v192
	v_mov_b32_e32 v216, v193
	v_mov_b32_e32 v217, v194
	v_mov_b32_e32 v218, v195
	v_cvt_f32_ubyte1_e32 v213, v188
	v_cvt_f32_ubyte0_e32 v212, v188
	v_cvt_f32_ubyte3_e32 v211, v188
	v_cvt_f32_ubyte0_e32 v0, v192
	v_rcp_iflag_f32_e32 v2, v0
	v_cvt_f32_ubyte1_e32 v0, v192
	v_rcp_iflag_f32_e32 v3, v0
	v_cvt_f32_ubyte2_e32 v0, v192
	v_rcp_iflag_f32_e32 v208, v0
	v_cvt_f32_ubyte3_e32 v0, v192
	v_rcp_iflag_f32_e32 v209, v0
	v_pk_mul_f32 v[2:3], v[2:3], v[212:213]
	v_cvt_f32_ubyte0_e32 v0, v193
	v_pk_mul_f32 v[128:129], v[128:129], v[2:3]
	v_rcp_iflag_f32_e32 v2, v0
	v_cvt_f32_ubyte1_e32 v0, v193
	v_rcp_iflag_f32_e32 v3, v0
	v_cvt_f32_ubyte2_e32 v210, v188
	v_cvt_f32_ubyte2_e32 v0, v193
	v_pk_mul_f32 v[208:209], v[208:209], v[210:211]
	v_rcp_iflag_f32_e32 v192, v0
	v_cvt_f32_ubyte3_e32 v0, v193
	v_cvt_f32_ubyte1_e32 v211, v189
	v_cvt_f32_ubyte0_e32 v210, v189
	v_rcp_iflag_f32_e32 v193, v0
	v_pk_mul_f32 v[2:3], v[2:3], v[210:211]
	v_cvt_f32_ubyte0_e32 v0, v194
	v_pk_mul_f32 v[124:125], v[124:125], v[2:3]
	v_rcp_iflag_f32_e32 v2, v0
	v_cvt_f32_ubyte1_e32 v0, v194
	v_rcp_iflag_f32_e32 v3, v0
	v_pk_mul_f32 v[130:131], v[130:131], v[208:209]
	v_cvt_f32_ubyte3_e32 v209, v189
	v_cvt_f32_ubyte2_e32 v208, v189
	v_pk_mul_f32 v[188:189], v[192:193], v[208:209]
	v_cvt_f32_ubyte2_e32 v0, v194
	v_pk_mul_f32 v[126:127], v[126:127], v[188:189]
	v_rcp_iflag_f32_e32 v188, v0
	v_cvt_f32_ubyte3_e32 v0, v194
	v_cvt_f32_ubyte1_e32 v209, v190
	v_cvt_f32_ubyte0_e32 v208, v190
	v_rcp_iflag_f32_e32 v189, v0
	v_pk_mul_f32 v[2:3], v[2:3], v[208:209]
	v_cvt_f32_ubyte0_e32 v0, v195
	v_pk_mul_f32 v[120:121], v[120:121], v[2:3]
	v_rcp_iflag_f32_e32 v2, v0
	v_cvt_f32_ubyte1_e32 v0, v195
	v_rcp_iflag_f32_e32 v3, v0
	v_cvt_f32_ubyte3_e32 v193, v190
	v_cvt_f32_ubyte2_e32 v192, v190
	v_pk_mul_f32 v[188:189], v[188:189], v[192:193]
	v_cvt_f32_ubyte2_e32 v0, v195
	v_pk_mul_f32 v[122:123], v[122:123], v[188:189]
	v_rcp_iflag_f32_e32 v188, v0
	v_cvt_f32_ubyte3_e32 v0, v195
	v_cvt_f32_ubyte1_e32 v195, v191
	v_cvt_f32_ubyte0_e32 v194, v191
	v_rcp_iflag_f32_e32 v189, v0
	v_pk_mul_f32 v[2:3], v[2:3], v[194:195]
	s_waitcnt vmcnt(6)
; __device__ __forceinline__ float ub0(unsigned w) { return (float)(w & 0xffu); }
; __device__ __forceinline__ float ub1(unsigned w) { return (float)((w >> 8) & 0xffu); }
; __device__ __forceinline__ float ub2(unsigned w) { return (float)((w >> 16) & 0xffu); }
; __device__ __forceinline__ float ub3(unsigned w) { return (float)(w >> 24); }
; __device__ __forceinline__ void gate_ratio4(f32x4& v, unsigned n, unsigned d) {
;     v[0] *= ub0(n) * __builtin_amdgcn_rcpf(ub0(d)); v[1] *= ub1(n) * __builtin_amdgcn_rcpf(ub1(d)); v[2] *= ub2(n) * __builtin_amdgcn_rcpf(ub2(d)); v[3] *= ub3(n) * __builtin_amdgcn_rcpf(ub3(d)); }
;     __device__ __forceinline__ void mid(f32x4 (&acc)[2][2][4][2], const pg8::GUnit& u, int b, int wr, int wc, int fr, int fq) const {
;     ...
;         for (int k = 0; k < 8; ++k) { const int ai = k >> 2, m = k & 3;
;             gate_ratio4(acc[ai][0][m][0], gn[k].x, gd[k].x); gate_ratio4(acc[ai][0][m][1], gn[k].y, gd[k].y); gate_ratio4(acc[ai][1][m][0], gn[k].z, gd[k].z); gate_ratio4(acc[ai][1][m][1], gn[k].w, gd[k].w); }
	v_mov_b32_e32 v219, v184
	v_mov_b32_e32 v220, v185
	v_mov_b32_e32 v221, v186
	v_mov_b32_e32 v222, v187
	v_cvt_f32_ubyte0_e32 v0, v184
	v_pk_mul_f32 v[116:117], v[116:117], v[2:3]
	v_rcp_iflag_f32_e32 v2, v0
	v_cvt_f32_ubyte1_e32 v0, v184
	v_rcp_iflag_f32_e32 v3, v0
	v_cvt_f32_ubyte3_e32 v193, v191
	v_cvt_f32_ubyte2_e32 v192, v191
	v_pk_mul_f32 v[188:189], v[188:189], v[192:193]
	v_cvt_f32_ubyte2_e32 v0, v184
	v_pk_mul_f32 v[118:119], v[118:119], v[188:189]
	v_rcp_iflag_f32_e32 v188, v0
	v_cvt_f32_ubyte3_e32 v0, v184
	v_cvt_f32_ubyte1_e32 v193, v180
	v_cvt_f32_ubyte0_e32 v192, v180
	v_rcp_iflag_f32_e32 v189, v0
	v_pk_mul_f32 v[2:3], v[2:3], v[192:193]
	v_cvt_f32_ubyte0_e32 v0, v185
	v_pk_mul_f32 v[112:113], v[112:113], v[2:3]
	v_rcp_iflag_f32_e32 v2, v0
	v_cvt_f32_ubyte1_e32 v0, v185
	v_rcp_iflag_f32_e32 v3, v0
	v_cvt_f32_ubyte3_e32 v191, v180
	v_cvt_f32_ubyte2_e32 v190, v180
	v_cvt_f32_ubyte2_e32 v0, v185
	v_pk_mul_f32 v[188:189], v[188:189], v[190:191]
	v_rcp_iflag_f32_e32 v184, v0
	v_cvt_f32_ubyte3_e32 v0, v185
	v_cvt_f32_ubyte1_e32 v191, v181
	v_cvt_f32_ubyte0_e32 v190, v181
	v_rcp_iflag_f32_e32 v185, v0
	v_pk_mul_f32 v[2:3], v[2:3], v[190:191]
	v_cvt_f32_ubyte0_e32 v0, v186
	v_pk_mul_f32 v[108:109], v[108:109], v[2:3]
	v_rcp_iflag_f32_e32 v2, v0
	v_cvt_f32_ubyte1_e32 v0, v186
	v_rcp_iflag_f32_e32 v3, v0
	v_pk_mul_f32 v[114:115], v[114:115], v[188:189]
	v_cvt_f32_ubyte3_e32 v189, v181
	v_cvt_f32_ubyte2_e32 v188, v181
	v_pk_mul_f32 v[180:181], v[184:185], v[188:189]
	v_cvt_f32_ubyte2_e32 v0, v186
	v_pk_mul_f32 v[110:111], v[110:111], v[180:181]
	v_rcp_iflag_f32_e32 v180, v0
	v_cvt_f32_ubyte3_e32 v0, v186
	v_cvt_f32_ubyte1_e32 v189, v182
	v_cvt_f32_ubyte0_e32 v188, v182
	v_rcp_iflag_f32_e32 v181, v0
	v_pk_mul_f32 v[2:3], v[2:3], v[188:189]
	v_cvt_f32_ubyte0_e32 v0, v187
	v_pk_mul_f32 v[104:105], v[104:105], v[2:3]
	v_rcp_iflag_f32_e32 v2, v0
	v_cvt_f32_ubyte1_e32 v0, v187
	v_rcp_iflag_f32_e32 v3, v0
	v_cvt_f32_ubyte3_e32 v185, v182
	v_cvt_f32_ubyte2_e32 v184, v182
	v_pk_mul_f32 v[180:181], v[180:181], v[184:185]
	v_cvt_f32_ubyte2_e32 v0, v187
	v_pk_mul_f32 v[106:107], v[106:107], v[180:181]
	v_rcp_iflag_f32_e32 v180, v0
	v_cvt_f32_ubyte3_e32 v0, v187
	v_cvt_f32_ubyte1_e32 v187, v183
	v_cvt_f32_ubyte0_e32 v186, v183
	v_rcp_iflag_f32_e32 v181, v0
	v_pk_mul_f32 v[2:3], v[2:3], v[186:187]
	s_waitcnt vmcnt(5)
	v_mov_b32_e32 v223, v176
	v_mov_b32_e32 v224, v177
	v_mov_b32_e32 v225, v178
	v_mov_b32_e32 v226, v179
	v_cvt_f32_ubyte0_e32 v0, v176
	v_pk_mul_f32 v[100:101], v[100:101], v[2:3]
	v_rcp_iflag_f32_e32 v2, v0
	v_cvt_f32_ubyte1_e32 v0, v176
	v_rcp_iflag_f32_e32 v3, v0
	v_cvt_f32_ubyte3_e32 v185, v183
	v_cvt_f32_ubyte2_e32 v184, v183
	v_pk_mul_f32 v[180:181], v[180:181], v[184:185]
	v_cvt_f32_ubyte2_e32 v0, v176
	v_pk_mul_f32 v[102:103], v[102:103], v[180:181]
	v_rcp_iflag_f32_e32 v180, v0
	v_cvt_f32_ubyte3_e32 v0, v176
	v_cvt_f32_ubyte1_e32 v185, v172
	v_cvt_f32_ubyte0_e32 v184, v172
	v_rcp_iflag_f32_e32 v181, v0
	v_pk_mul_f32 v[2:3], v[2:3], v[184:185]
	v_cvt_f32_ubyte0_e32 v0, v177
	v_pk_mul_f32 v[96:97], v[96:97], v[2:3]
	v_rcp_iflag_f32_e32 v2, v0
	v_cvt_f32_ubyte1_e32 v0, v177
	v_rcp_iflag_f32_e32 v3, v0
	v_cvt_f32_ubyte3_e32 v183, v172
	v_cvt_f32_ubyte2_e32 v182, v172
	v_cvt_f32_ubyte2_e32 v0, v177
	v_pk_mul_f32 v[180:181], v[180:181], v[182:183]
	v_rcp_iflag_f32_e32 v176, v0
	v_cvt_f32_ubyte3_e32 v0, v177
	v_cvt_f32_ubyte1_e32 v183, v173
	v_cvt_f32_ubyte0_e32 v182, v173
	v_rcp_iflag_f32_e32 v177, v0
	v_pk_mul_f32 v[2:3], v[2:3], v[182:183]
	v_cvt_f32_ubyte0_e32 v0, v178
	v_pk_mul_f32 v[92:93], v[92:93], v[2:3]
	v_rcp_iflag_f32_e32 v2, v0
	v_cvt_f32_ubyte1_e32 v0, v178
	v_rcp_iflag_f32_e32 v3, v0
	v_pk_mul_f32 v[98:99], v[98:99], v[180:181]
	v_cvt_f32_ubyte3_e32 v181, v173
	v_cvt_f32_ubyte2_e32 v180, v173
	v_pk_mul_f32 v[172:173], v[176:177], v[180:181]
	v_cvt_f32_ubyte2_e32 v0, v178
	v_pk_mul_f32 v[94:95], v[94:95], v[172:173]
	v_rcp_iflag_f32_e32 v172, v0
	v_cvt_f32_ubyte3_e32 v0, v178
	v_cvt_f32_ubyte1_e32 v181, v174
	v_cvt_f32_ubyte0_e32 v180, v174
	v_rcp_iflag_f32_e32 v173, v0
	v_pk_mul_f32 v[2:3], v[2:3], v[180:181]
	v_cvt_f32_ubyte0_e32 v0, v179
	v_pk_mul_f32 v[88:89], v[88:89], v[2:3]
	v_rcp_iflag_f32_e32 v2, v0
	v_cvt_f32_ubyte1_e32 v0, v179
	v_rcp_iflag_f32_e32 v3, v0
	v_cvt_f32_ubyte3_e32 v177, v174
	v_cvt_f32_ubyte2_e32 v176, v174
	v_pk_mul_f32 v[172:173], v[172:173], v[176:177]
	v_cvt_f32_ubyte2_e32 v0, v179
	v_pk_mul_f32 v[90:91], v[90:91], v[172:173]
	v_rcp_iflag_f32_e32 v172, v0
	v_cvt_f32_ubyte3_e32 v0, v179
	v_cvt_f32_ubyte1_e32 v179, v175
	v_cvt_f32_ubyte0_e32 v178, v175
	v_rcp_iflag_f32_e32 v173, v0
	v_pk_mul_f32 v[2:3], v[2:3], v[178:179]
	s_waitcnt vmcnt(4)
; __device__ __forceinline__ float ub0(unsigned w) { return (float)(w & 0xffu); }
; __device__ __forceinline__ float ub1(unsigned w) { return (float)((w >> 8) & 0xffu); }
; __device__ __forceinline__ float ub2(unsigned w) { return (float)((w >> 16) & 0xffu); }
; __device__ __forceinline__ float ub3(unsigned w) { return (float)(w >> 24); }
; __device__ __forceinline__ void gate_ratio4(f32x4& v, unsigned n, unsigned d) {
;     v[0] *= ub0(n) * __builtin_amdgcn_rcpf(ub0(d)); v[1] *= ub1(n) * __builtin_amdgcn_rcpf(ub1(d)); v[2] *= ub2(n) * __builtin_amdgcn_rcpf(ub2(d)); v[3] *= ub3(n) * __builtin_amdgcn_rcpf(ub3(d)); }
;     __device__ __forceinline__ void mid(f32x4 (&acc)[2][2][4][2], const pg8::GUnit& u, int b, int wr, int wc, int fr, int fq) const {
;     ...
;         for (int k = 0; k < 8; ++k) { const int ai = k >> 2, m = k & 3;
;             gate_ratio4(acc[ai][0][m][0], gn[k].x, gd[k].x); gate_ratio4(acc[ai][0][m][1], gn[k].y, gd[k].y); gate_ratio4(acc[ai][1][m][0], gn[k].z, gd[k].z); gate_ratio4(acc[ai][1][m][1], gn[k].w, gd[k].w); }
	v_mov_b32_e32 v227, v168
	v_mov_b32_e32 v228, v169
	v_mov_b32_e32 v229, v170
	v_mov_b32_e32 v230, v171
	v_cvt_f32_ubyte0_e32 v0, v168
	v_pk_mul_f32 v[84:85], v[84:85], v[2:3]
	v_rcp_iflag_f32_e32 v2, v0
	v_cvt_f32_ubyte1_e32 v0, v168
	v_rcp_iflag_f32_e32 v3, v0
	v_cvt_f32_ubyte3_e32 v177, v175
	v_cvt_f32_ubyte2_e32 v176, v175
	v_pk_mul_f32 v[172:173], v[172:173], v[176:177]
	v_cvt_f32_ubyte2_e32 v0, v168
	v_pk_mul_f32 v[86:87], v[86:87], v[172:173]
	v_rcp_iflag_f32_e32 v172, v0
	v_cvt_f32_ubyte3_e32 v0, v168
	v_cvt_f32_ubyte1_e32 v177, v164
	v_cvt_f32_ubyte0_e32 v176, v164
	v_rcp_iflag_f32_e32 v173, v0
	v_pk_mul_f32 v[2:3], v[2:3], v[176:177]
	v_cvt_f32_ubyte0_e32 v0, v169
	v_pk_mul_f32 v[80:81], v[80:81], v[2:3]
	v_rcp_iflag_f32_e32 v2, v0
	v_cvt_f32_ubyte1_e32 v0, v169
	v_rcp_iflag_f32_e32 v3, v0
	v_cvt_f32_ubyte3_e32 v175, v164
	v_cvt_f32_ubyte2_e32 v174, v164
	v_cvt_f32_ubyte2_e32 v0, v169
	v_pk_mul_f32 v[172:173], v[172:173], v[174:175]
	v_rcp_iflag_f32_e32 v168, v0
	v_cvt_f32_ubyte3_e32 v0, v169
	v_cvt_f32_ubyte1_e32 v175, v165
	v_cvt_f32_ubyte0_e32 v174, v165
	v_rcp_iflag_f32_e32 v169, v0
	v_pk_mul_f32 v[2:3], v[2:3], v[174:175]
	v_cvt_f32_ubyte0_e32 v0, v170
	v_pk_mul_f32 v[76:77], v[76:77], v[2:3]
	v_rcp_iflag_f32_e32 v2, v0
	v_cvt_f32_ubyte1_e32 v0, v170
	v_rcp_iflag_f32_e32 v3, v0
	v_pk_mul_f32 v[82:83], v[82:83], v[172:173]
	v_cvt_f32_ubyte3_e32 v173, v165
	v_cvt_f32_ubyte2_e32 v172, v165
	v_pk_mul_f32 v[164:165], v[168:169], v[172:173]
	v_cvt_f32_ubyte2_e32 v0, v170
	v_pk_mul_f32 v[78:79], v[78:79], v[164:165]
	v_rcp_iflag_f32_e32 v164, v0
	v_cvt_f32_ubyte3_e32 v0, v170
	v_cvt_f32_ubyte1_e32 v173, v166
	v_cvt_f32_ubyte0_e32 v172, v166
	v_rcp_iflag_f32_e32 v165, v0
	v_pk_mul_f32 v[2:3], v[2:3], v[172:173]
	v_cvt_f32_ubyte0_e32 v0, v171
	v_pk_mul_f32 v[72:73], v[72:73], v[2:3]
	v_rcp_iflag_f32_e32 v2, v0
	v_cvt_f32_ubyte1_e32 v0, v171
	v_rcp_iflag_f32_e32 v3, v0
	v_cvt_f32_ubyte3_e32 v169, v166
	v_cvt_f32_ubyte2_e32 v168, v166
	v_pk_mul_f32 v[164:165], v[164:165], v[168:169]
	v_cvt_f32_ubyte2_e32 v0, v171
	v_pk_mul_f32 v[74:75], v[74:75], v[164:165]
	v_rcp_iflag_f32_e32 v164, v0
	v_cvt_f32_ubyte3_e32 v0, v171
	v_cvt_f32_ubyte1_e32 v171, v167
	v_cvt_f32_ubyte0_e32 v170, v167
	v_rcp_iflag_f32_e32 v165, v0
	v_pk_mul_f32 v[2:3], v[2:3], v[170:171]
	s_waitcnt vmcnt(3)
	v_mov_b32_e32 v231, v160
	v_mov_b32_e32 v232, v161
	v_mov_b32_e32 v233, v162
	v_mov_b32_e32 v234, v163
	v_cvt_f32_ubyte0_e32 v0, v160
	v_pk_mul_f32 v[68:69], v[68:69], v[2:3]
	v_rcp_iflag_f32_e32 v2, v0
	v_cvt_f32_ubyte1_e32 v0, v160
	v_rcp_iflag_f32_e32 v3, v0
	v_cvt_f32_ubyte3_e32 v169, v167
	v_cvt_f32_ubyte2_e32 v168, v167
	v_pk_mul_f32 v[164:165], v[164:165], v[168:169]
	v_cvt_f32_ubyte2_e32 v0, v160
	v_pk_mul_f32 v[70:71], v[70:71], v[164:165]
	v_rcp_iflag_f32_e32 v164, v0
	v_cvt_f32_ubyte3_e32 v0, v160
	v_cvt_f32_ubyte1_e32 v169, v156
	v_cvt_f32_ubyte0_e32 v168, v156
	v_rcp_iflag_f32_e32 v165, v0
	v_pk_mul_f32 v[2:3], v[2:3], v[168:169]
	v_cvt_f32_ubyte0_e32 v0, v161
	v_pk_mul_f32 v[64:65], v[64:65], v[2:3]
	v_rcp_iflag_f32_e32 v2, v0
	v_cvt_f32_ubyte1_e32 v0, v161
	v_rcp_iflag_f32_e32 v3, v0
	v_cvt_f32_ubyte3_e32 v167, v156
	v_cvt_f32_ubyte2_e32 v166, v156
	v_cvt_f32_ubyte2_e32 v0, v161
	v_pk_mul_f32 v[164:165], v[164:165], v[166:167]
	v_rcp_iflag_f32_e32 v160, v0
	v_cvt_f32_ubyte3_e32 v0, v161
	v_cvt_f32_ubyte1_e32 v167, v157
	v_cvt_f32_ubyte0_e32 v166, v157
	v_rcp_iflag_f32_e32 v161, v0
	v_pk_mul_f32 v[2:3], v[2:3], v[166:167]
	v_cvt_f32_ubyte0_e32 v0, v162
	v_pk_mul_f32 v[60:61], v[60:61], v[2:3]
	v_rcp_iflag_f32_e32 v2, v0
	v_cvt_f32_ubyte1_e32 v0, v162
	v_rcp_iflag_f32_e32 v3, v0
	v_pk_mul_f32 v[66:67], v[66:67], v[164:165]
	v_cvt_f32_ubyte3_e32 v165, v157
	v_cvt_f32_ubyte2_e32 v164, v157
	v_pk_mul_f32 v[156:157], v[160:161], v[164:165]
	v_cvt_f32_ubyte2_e32 v0, v162
	v_pk_mul_f32 v[62:63], v[62:63], v[156:157]
	v_rcp_iflag_f32_e32 v156, v0
	v_cvt_f32_ubyte3_e32 v0, v162
	v_cvt_f32_ubyte1_e32 v165, v158
	v_cvt_f32_ubyte0_e32 v164, v158
	v_rcp_iflag_f32_e32 v157, v0
	v_pk_mul_f32 v[2:3], v[2:3], v[164:165]
	v_cvt_f32_ubyte0_e32 v0, v163
	v_pk_mul_f32 v[56:57], v[56:57], v[2:3]
	v_rcp_iflag_f32_e32 v2, v0
	v_cvt_f32_ubyte1_e32 v0, v163
	v_rcp_iflag_f32_e32 v3, v0
	v_cvt_f32_ubyte3_e32 v161, v158
	v_cvt_f32_ubyte2_e32 v160, v158
	v_pk_mul_f32 v[156:157], v[156:157], v[160:161]
	v_cvt_f32_ubyte2_e32 v0, v163
	v_pk_mul_f32 v[58:59], v[58:59], v[156:157]
	v_rcp_iflag_f32_e32 v156, v0
	v_cvt_f32_ubyte3_e32 v0, v163
	v_cvt_f32_ubyte1_e32 v163, v159
	v_cvt_f32_ubyte0_e32 v162, v159
	v_rcp_iflag_f32_e32 v157, v0
	v_pk_mul_f32 v[2:3], v[2:3], v[162:163]
	s_waitcnt vmcnt(2)
; __device__ __forceinline__ float ub0(unsigned w) { return (float)(w & 0xffu); }
; __device__ __forceinline__ float ub1(unsigned w) { return (float)((w >> 8) & 0xffu); }
; __device__ __forceinline__ float ub2(unsigned w) { return (float)((w >> 16) & 0xffu); }
; __device__ __forceinline__ float ub3(unsigned w) { return (float)(w >> 24); }
; __device__ __forceinline__ void gate_ratio4(f32x4& v, unsigned n, unsigned d) {
;     v[0] *= ub0(n) * __builtin_amdgcn_rcpf(ub0(d)); v[1] *= ub1(n) * __builtin_amdgcn_rcpf(ub1(d)); v[2] *= ub2(n) * __builtin_amdgcn_rcpf(ub2(d)); v[3] *= ub3(n) * __builtin_amdgcn_rcpf(ub3(d)); }
;     __device__ __forceinline__ void mid(f32x4 (&acc)[2][2][4][2], const pg8::GUnit& u, int b, int wr, int wc, int fr, int fq) const {
;     ...
;         for (int k = 0; k < 8; ++k) { const int ai = k >> 2, m = k & 3;
;             gate_ratio4(acc[ai][0][m][0], gn[k].x, gd[k].x); gate_ratio4(acc[ai][0][m][1], gn[k].y, gd[k].y); gate_ratio4(acc[ai][1][m][0], gn[k].z, gd[k].z); gate_ratio4(acc[ai][1][m][1], gn[k].w, gd[k].w); }
	v_mov_b32_e32 v235, v152
	v_mov_b32_e32 v236, v153
	v_mov_b32_e32 v237, v154
	v_mov_b32_e32 v238, v155
	v_cvt_f32_ubyte0_e32 v0, v152
	v_pk_mul_f32 v[52:53], v[52:53], v[2:3]
	v_rcp_iflag_f32_e32 v2, v0
	v_cvt_f32_ubyte1_e32 v0, v152
	v_rcp_iflag_f32_e32 v3, v0
	v_cvt_f32_ubyte3_e32 v161, v159
	v_cvt_f32_ubyte2_e32 v160, v159
	v_pk_mul_f32 v[156:157], v[156:157], v[160:161]
	v_cvt_f32_ubyte2_e32 v0, v152
	v_pk_mul_f32 v[54:55], v[54:55], v[156:157]
	v_rcp_iflag_f32_e32 v156, v0
	v_cvt_f32_ubyte3_e32 v0, v152
	v_cvt_f32_ubyte1_e32 v161, v148
	v_cvt_f32_ubyte0_e32 v160, v148
	v_rcp_iflag_f32_e32 v157, v0
	v_pk_mul_f32 v[2:3], v[2:3], v[160:161]
	v_cvt_f32_ubyte0_e32 v0, v153
	v_pk_mul_f32 v[48:49], v[48:49], v[2:3]
	v_rcp_iflag_f32_e32 v2, v0
	v_cvt_f32_ubyte1_e32 v0, v153
	v_rcp_iflag_f32_e32 v3, v0
	v_cvt_f32_ubyte3_e32 v159, v148
	v_cvt_f32_ubyte2_e32 v158, v148
	v_cvt_f32_ubyte2_e32 v0, v153
	v_pk_mul_f32 v[156:157], v[156:157], v[158:159]
	v_rcp_iflag_f32_e32 v152, v0
	v_cvt_f32_ubyte3_e32 v0, v153
	v_cvt_f32_ubyte1_e32 v159, v149
	v_cvt_f32_ubyte0_e32 v158, v149
	v_rcp_iflag_f32_e32 v153, v0
	v_pk_mul_f32 v[2:3], v[2:3], v[158:159]
	v_cvt_f32_ubyte0_e32 v0, v154
	v_pk_mul_f32 v[44:45], v[44:45], v[2:3]
	v_rcp_iflag_f32_e32 v2, v0
	v_cvt_f32_ubyte1_e32 v0, v154
	v_rcp_iflag_f32_e32 v3, v0
	v_pk_mul_f32 v[50:51], v[50:51], v[156:157]
	v_cvt_f32_ubyte3_e32 v157, v149
	v_cvt_f32_ubyte2_e32 v156, v149
	v_pk_mul_f32 v[148:149], v[152:153], v[156:157]
	v_cvt_f32_ubyte2_e32 v0, v154
	v_pk_mul_f32 v[46:47], v[46:47], v[148:149]
	v_rcp_iflag_f32_e32 v148, v0
	v_cvt_f32_ubyte3_e32 v0, v154
	v_cvt_f32_ubyte1_e32 v157, v150
	v_cvt_f32_ubyte0_e32 v156, v150
	v_rcp_iflag_f32_e32 v149, v0
	v_pk_mul_f32 v[2:3], v[2:3], v[156:157]
	v_cvt_f32_ubyte0_e32 v0, v155
	v_pk_mul_f32 v[40:41], v[40:41], v[2:3]
	v_rcp_iflag_f32_e32 v2, v0
	v_cvt_f32_ubyte1_e32 v0, v155
	v_rcp_iflag_f32_e32 v3, v0
	v_cvt_f32_ubyte3_e32 v153, v150
	v_cvt_f32_ubyte2_e32 v152, v150
	v_pk_mul_f32 v[148:149], v[148:149], v[152:153]
	v_cvt_f32_ubyte2_e32 v0, v155
	v_pk_mul_f32 v[42:43], v[42:43], v[148:149]
	v_rcp_iflag_f32_e32 v148, v0
	v_cvt_f32_ubyte3_e32 v0, v155
	v_cvt_f32_ubyte1_e32 v155, v151
	v_cvt_f32_ubyte0_e32 v154, v151
	v_rcp_iflag_f32_e32 v149, v0
	v_pk_mul_f32 v[2:3], v[2:3], v[154:155]
	s_waitcnt vmcnt(1)
	v_mov_b32_e32 v239, v144
	v_mov_b32_e32 v240, v145
	v_mov_b32_e32 v241, v146
	v_mov_b32_e32 v242, v147
	v_cvt_f32_ubyte0_e32 v0, v144
	v_pk_mul_f32 v[36:37], v[36:37], v[2:3]
	v_rcp_iflag_f32_e32 v2, v0
	v_cvt_f32_ubyte1_e32 v0, v144
	v_rcp_iflag_f32_e32 v3, v0
	v_cvt_f32_ubyte3_e32 v153, v151
	v_cvt_f32_ubyte2_e32 v152, v151
	v_pk_mul_f32 v[148:149], v[148:149], v[152:153]
	v_cvt_f32_ubyte2_e32 v0, v144
	v_pk_mul_f32 v[38:39], v[38:39], v[148:149]
	v_rcp_iflag_f32_e32 v148, v0
	v_cvt_f32_ubyte3_e32 v0, v144
	v_cvt_f32_ubyte1_e32 v153, v140
	v_cvt_f32_ubyte0_e32 v152, v140
	v_rcp_iflag_f32_e32 v149, v0
	v_pk_mul_f32 v[2:3], v[2:3], v[152:153]
	v_cvt_f32_ubyte0_e32 v0, v145
	v_pk_mul_f32 v[32:33], v[32:33], v[2:3]
	v_rcp_iflag_f32_e32 v2, v0
	v_cvt_f32_ubyte1_e32 v0, v145
	v_rcp_iflag_f32_e32 v3, v0
	v_cvt_f32_ubyte3_e32 v151, v140
	v_cvt_f32_ubyte2_e32 v150, v140
	v_cvt_f32_ubyte2_e32 v0, v145
	v_pk_mul_f32 v[148:149], v[148:149], v[150:151]
	v_rcp_iflag_f32_e32 v144, v0
	v_cvt_f32_ubyte3_e32 v0, v145
	v_cvt_f32_ubyte1_e32 v151, v141
	v_cvt_f32_ubyte0_e32 v150, v141
	v_rcp_iflag_f32_e32 v145, v0
	v_pk_mul_f32 v[2:3], v[2:3], v[150:151]
	v_cvt_f32_ubyte0_e32 v0, v146
	v_pk_mul_f32 v[28:29], v[28:29], v[2:3]
	v_rcp_iflag_f32_e32 v2, v0
	v_cvt_f32_ubyte1_e32 v0, v146
	v_rcp_iflag_f32_e32 v3, v0
	v_pk_mul_f32 v[34:35], v[34:35], v[148:149]
	v_cvt_f32_ubyte3_e32 v149, v141
	v_cvt_f32_ubyte2_e32 v148, v141
	v_pk_mul_f32 v[140:141], v[144:145], v[148:149]
	v_cvt_f32_ubyte2_e32 v0, v146
	v_pk_mul_f32 v[30:31], v[30:31], v[140:141]
	v_rcp_iflag_f32_e32 v140, v0
	v_cvt_f32_ubyte3_e32 v0, v146
	v_cvt_f32_ubyte1_e32 v149, v142
	v_cvt_f32_ubyte0_e32 v148, v142
	v_rcp_iflag_f32_e32 v141, v0
	v_pk_mul_f32 v[2:3], v[2:3], v[148:149]
	v_cvt_f32_ubyte0_e32 v0, v147
	v_pk_mul_f32 v[24:25], v[24:25], v[2:3]
	v_rcp_iflag_f32_e32 v2, v0
	v_cvt_f32_ubyte1_e32 v0, v147
	v_rcp_iflag_f32_e32 v3, v0
	v_cvt_f32_ubyte3_e32 v145, v142
	v_cvt_f32_ubyte2_e32 v144, v142
	v_pk_mul_f32 v[140:141], v[140:141], v[144:145]
	v_cvt_f32_ubyte2_e32 v0, v147
	v_pk_mul_f32 v[26:27], v[26:27], v[140:141]
	v_rcp_iflag_f32_e32 v140, v0
	v_cvt_f32_ubyte3_e32 v0, v147
	v_cvt_f32_ubyte1_e32 v147, v143
	v_cvt_f32_ubyte0_e32 v146, v143
	v_rcp_iflag_f32_e32 v141, v0
	v_pk_mul_f32 v[2:3], v[2:3], v[146:147]
	s_waitcnt vmcnt(0)
; __device__ __forceinline__ float ub0(unsigned w) { return (float)(w & 0xffu); }
; __device__ __forceinline__ float ub1(unsigned w) { return (float)((w >> 8) & 0xffu); }
; __device__ __forceinline__ float ub2(unsigned w) { return (float)((w >> 16) & 0xffu); }
; __device__ __forceinline__ float ub3(unsigned w) { return (float)(w >> 24); }
; __device__ __forceinline__ void gate_ratio4(f32x4& v, unsigned n, unsigned d) {
;     v[0] *= ub0(n) * __builtin_amdgcn_rcpf(ub0(d)); v[1] *= ub1(n) * __builtin_amdgcn_rcpf(ub1(d)); v[2] *= ub2(n) * __builtin_amdgcn_rcpf(ub2(d)); v[3] *= ub3(n) * __builtin_amdgcn_rcpf(ub3(d)); }
;     __device__ __forceinline__ void mid(f32x4 (&acc)[2][2][4][2], const pg8::GUnit& u, int b, int wr, int wc, int fr, int fq) const {
;     ...
;         for (int k = 0; k < 8; ++k) { const int ai = k >> 2, m = k & 3;
;             gate_ratio4(acc[ai][0][m][0], gn[k].x, gd[k].x); gate_ratio4(acc[ai][0][m][1], gn[k].y, gd[k].y); gate_ratio4(acc[ai][1][m][0], gn[k].z, gd[k].z); gate_ratio4(acc[ai][1][m][1], gn[k].w, gd[k].w); }
	v_mov_b32_e32 v243, v136
	v_mov_b32_e32 v245, v137
	v_mov_b32_e32 v246, v138
	v_mov_b32_e32 v247, v139
	v_cvt_f32_ubyte0_e32 v0, v136
	v_pk_mul_f32 v[20:21], v[20:21], v[2:3]
	v_rcp_iflag_f32_e32 v2, v0
	v_cvt_f32_ubyte1_e32 v0, v136
	v_rcp_iflag_f32_e32 v3, v0
	v_cvt_f32_ubyte3_e32 v145, v143
	v_cvt_f32_ubyte2_e32 v144, v143
	v_pk_mul_f32 v[140:141], v[140:141], v[144:145]
	v_cvt_f32_ubyte2_e32 v0, v136
	v_pk_mul_f32 v[22:23], v[22:23], v[140:141]
	v_rcp_iflag_f32_e32 v140, v0
	v_cvt_f32_ubyte3_e32 v0, v136
	v_cvt_f32_ubyte1_e32 v145, v132
	v_cvt_f32_ubyte0_e32 v144, v132
	v_rcp_iflag_f32_e32 v141, v0
	v_pk_mul_f32 v[2:3], v[2:3], v[144:145]
	v_cvt_f32_ubyte0_e32 v0, v137
	v_pk_mul_f32 v[16:17], v[16:17], v[2:3]
	v_rcp_iflag_f32_e32 v2, v0
	v_cvt_f32_ubyte1_e32 v0, v137
	v_rcp_iflag_f32_e32 v3, v0
	v_cvt_f32_ubyte2_e32 v0, v137
	v_rcp_iflag_f32_e32 v136, v0
	v_cvt_f32_ubyte3_e32 v0, v137
	v_cvt_f32_ubyte3_e32 v143, v132
	v_cvt_f32_ubyte2_e32 v142, v132
	v_rcp_iflag_f32_e32 v137, v0
	v_pk_mul_f32 v[140:141], v[140:141], v[142:143]
	v_cvt_f32_ubyte1_e32 v143, v133
	v_cvt_f32_ubyte0_e32 v142, v133
	v_pk_mul_f32 v[2:3], v[2:3], v[142:143]
	v_cvt_f32_ubyte0_e32 v0, v138
	v_pk_mul_f32 v[18:19], v[18:19], v[140:141]
	v_cvt_f32_ubyte3_e32 v141, v133
	v_cvt_f32_ubyte2_e32 v140, v133
	v_pk_mul_f32 v[12:13], v[12:13], v[2:3]
	v_rcp_iflag_f32_e32 v2, v0
	v_cvt_f32_ubyte1_e32 v0, v138
	v_pk_mul_f32 v[132:133], v[136:137], v[140:141]
	v_rcp_iflag_f32_e32 v3, v0
	v_cvt_f32_ubyte2_e32 v0, v138
	v_pk_mul_f32 v[14:15], v[14:15], v[132:133]
	v_rcp_iflag_f32_e32 v132, v0
	v_cvt_f32_ubyte3_e32 v0, v138
	v_rcp_iflag_f32_e32 v133, v0
	v_cvt_f32_ubyte1_e32 v141, v134
	v_cvt_f32_ubyte0_e32 v140, v134
	v_pk_mul_f32 v[2:3], v[2:3], v[140:141]
	v_cvt_f32_ubyte0_e32 v0, v139
	v_cvt_f32_ubyte3_e32 v137, v134
	v_cvt_f32_ubyte2_e32 v136, v134
	v_pk_mul_f32 v[8:9], v[8:9], v[2:3]
	v_rcp_iflag_f32_e32 v2, v0
	v_cvt_f32_ubyte1_e32 v0, v139
	v_pk_mul_f32 v[132:133], v[132:133], v[136:137]
	v_rcp_iflag_f32_e32 v3, v0
	v_cvt_f32_ubyte2_e32 v0, v139
	v_pk_mul_f32 v[10:11], v[10:11], v[132:133]
	v_rcp_iflag_f32_e32 v132, v0
	v_cvt_f32_ubyte3_e32 v0, v139
	v_rcp_iflag_f32_e32 v133, v0
	v_cvt_f32_ubyte3_e32 v137, v135
	v_cvt_f32_ubyte2_e32 v136, v135
	v_cvt_f32_ubyte1_e32 v139, v135
	v_cvt_f32_ubyte0_e32 v138, v135
	v_pk_mul_f32 v[2:3], v[2:3], v[138:139]
	v_pk_mul_f32 v[132:133], v[132:133], v[136:137]
	v_pk_mul_f32 v[4:5], v[4:5], v[2:3]
	v_pk_mul_f32 v[6:7], v[6:7], v[132:133]
	s_branch .LBB0_785

; #define GAS __attribute__((address_space(1)))
;     __device__ __forceinline__ void mid(f32x4 (&acc)[2][2][4][2], const pg8::GUnit& u, int b, int wr, int wc, int fr, int fq) const {
;     ...
;         const GAS unsigned char* gp = (const GAS unsigned char*)P + (size_t)(u.pm * 256 + (wr * 4 + wc) * 32 + fq) * (INW * 2) + (GA * 2 + (b * 16 + u.pn) * 256 + fr * 16);
;         u32x4 gn[8], gd[8];
; #pragma unroll
;         for (int k = 0; k < 8; ++k) { const GAS unsigned char* q = gp + (size_t)(k * 4) * (INW * 2); gn[k] = *(const GAS u32x4*)q; gd[k] = *(const GAS u32x4*)(q + DM); }
; #pragma unroll
;         for (int k = 0; k < 8; ++k) { const int ai = k >> 2, m = k & 3;
;             gate_ratio4(acc[ai][0][m][0], gn[k].x, gd[k].x); gate_ratio4(acc[ai][0][m][1], gn[k].y, gd[k].y); gate_ratio4(acc[ai][1][m][0], gn[k].z, gd[k].z); gate_ratio4(acc[ai][1][m][1], gn[k].w, gd[k].w); }
.LBB0_783:
	s_andn2_b64 vcc, exec, s[8:9]
	s_cbranch_vccnz .LBB0_785
	v_mbcnt_lo_u32_b32 v0, -1, 0
	v_mbcnt_hi_u32_b32 v0, -1, v0
	s_cmpk_lg_i32 s89, 0xc00
	s_cbranch_scc1 .Lbr_mid1_load
	s_cmpk_eq_i32 s89, 0xc00
	v_ashrrev_i32_e32 v2, 4, v0
	v_add_u32_e32 v2, s84, v2
	v_mad_i64_i32 v[2:3], s[8:9], v2, s93, v[200:201]
	s_cselect_b32 s8, 0, 0x1000
	v_lshlrev_b32_e32 v0, 4, v0
	s_add_i32 s8, s87, s8
	v_and_b32_e32 v0, 0xf0, v0
	v_or_b32_e32 v132, s8, v0
	v_ashrrev_i32_e32 v133, 31, v132
	v_lshl_add_u64 v[2:3], v[2:3], 0, v[132:133]
	v_add_co_u32_e32 v132, vcc, s35, v2
	global_load_dwordx4 v[188:191], v[2:3], off
	s_nop 0
	v_addc_co_u32_e32 v133, vcc, 0, v3, vcc
	global_load_dwordx4 v[192:195], v[132:133], off
	s_mov_b32 s8, 0x31000
	v_add_co_u32_e32 v132, vcc, s8, v2
	s_mov_b32 s8, 0x61000
	s_nop 0
	v_addc_co_u32_e32 v133, vcc, 0, v3, vcc
	global_load_dwordx4 v[180:183], v[132:133], off offset:-4096
	global_load_dwordx4 v[184:187], v[132:133], off
	v_add_co_u32_e32 v132, vcc, s8, v2
	s_mov_b32 s8, 0x91000
	s_nop 0
	v_addc_co_u32_e32 v133, vcc, 0, v3, vcc
	global_load_dwordx4 v[172:175], v[132:133], off offset:-4096
	global_load_dwordx4 v[176:179], v[132:133], off
	v_add_co_u32_e32 v132, vcc, s8, v2
	s_mov_b32 s8, 0xc1000
	s_nop 0
	v_addc_co_u32_e32 v133, vcc, 0, v3, vcc
	global_load_dwordx4 v[164:167], v[132:133], off offset:-4096
	global_load_dwordx4 v[168:171], v[132:133], off
	v_add_co_u32_e32 v132, vcc, s8, v2
	s_mov_b32 s8, 0xf1000
	s_nop 0
	v_addc_co_u32_e32 v133, vcc, 0, v3, vcc
	global_load_dwordx4 v[156:159], v[132:133], off offset:-4096
	global_load_dwordx4 v[160:163], v[132:133], off
	v_add_co_u32_e32 v132, vcc, s8, v2
	s_mov_b32 s8, 0x121000
	s_nop 0
	v_addc_co_u32_e32 v133, vcc, 0, v3, vcc
	global_load_dwordx4 v[148:151], v[132:133], off offset:-4096
	global_load_dwordx4 v[152:155], v[132:133], off
	v_add_co_u32_e32 v132, vcc, s8, v2
	s_mov_b32 s8, 0x151000
	s_nop 0
	v_addc_co_u32_e32 v133, vcc, 0, v3, vcc
	v_add_co_u32_e32 v2, vcc, s8, v2
	global_load_dwordx4 v[140:143], v[132:133], off offset:-4096
	global_load_dwordx4 v[144:147], v[132:133], off
	v_addc_co_u32_e32 v3, vcc, 0, v3, vcc
	global_load_dwordx4 v[132:135], v[2:3], off offset:-4096
	global_load_dwordx4 v[136:139], v[2:3], off
	s_waitcnt vmcnt(14)
	v_mov_b32_e32 v215, v192
	v_mov_b32_e32 v216, v193
	v_mov_b32_e32 v217, v194
	v_mov_b32_e32 v218, v195
	v_cvt_f32_ubyte1_e32 v213, v188
	v_cvt_f32_ubyte0_e32 v212, v188
	v_cvt_f32_ubyte3_e32 v211, v188
	v_cvt_f32_ubyte0_e32 v0, v192
	v_rcp_iflag_f32_e32 v2, v0
	v_cvt_f32_ubyte1_e32 v0, v192
	v_rcp_iflag_f32_e32 v3, v0
	v_cvt_f32_ubyte2_e32 v0, v192
	v_rcp_iflag_f32_e32 v208, v0
	v_cvt_f32_ubyte3_e32 v0, v192
	v_rcp_iflag_f32_e32 v209, v0
	v_pk_mul_f32 v[2:3], v[2:3], v[212:213]
	v_cvt_f32_ubyte0_e32 v0, v193
	v_pk_mul_f32 v[128:129], v[128:129], v[2:3]
	v_rcp_iflag_f32_e32 v2, v0
	v_cvt_f32_ubyte1_e32 v0, v193
	v_rcp_iflag_f32_e32 v3, v0
	v_cvt_f32_ubyte2_e32 v210, v188
	v_cvt_f32_ubyte2_e32 v0, v193
	v_pk_mul_f32 v[208:209], v[208:209], v[210:211]
	v_rcp_iflag_f32_e32 v192, v0
	v_cvt_f32_ubyte3_e32 v0, v193
	v_cvt_f32_ubyte1_e32 v211, v189
	v_cvt_f32_ubyte0_e32 v210, v189
	v_rcp_iflag_f32_e32 v193, v0
	v_pk_mul_f32 v[2:3], v[2:3], v[210:211]
	v_cvt_f32_ubyte0_e32 v0, v194
	v_pk_mul_f32 v[124:125], v[124:125], v[2:3]
	v_rcp_iflag_f32_e32 v2, v0
	v_cvt_f32_ubyte1_e32 v0, v194
	v_rcp_iflag_f32_e32 v3, v0
	v_pk_mul_f32 v[130:131], v[130:131], v[208:209]
	v_cvt_f32_ubyte3_e32 v209, v189
	v_cvt_f32_ubyte2_e32 v208, v189
	v_pk_mul_f32 v[188:189], v[192:193], v[208:209]
	v_cvt_f32_ubyte2_e32 v0, v194
	v_pk_mul_f32 v[126:127], v[126:127], v[188:189]
	v_rcp_iflag_f32_e32 v188, v0
	v_cvt_f32_ubyte3_e32 v0, v194
	v_cvt_f32_ubyte1_e32 v209, v190
	v_cvt_f32_ubyte0_e32 v208, v190
	v_rcp_iflag_f32_e32 v189, v0
	v_pk_mul_f32 v[2:3], v[2:3], v[208:209]
	v_cvt_f32_ubyte0_e32 v0, v195
	v_pk_mul_f32 v[120:121], v[120:121], v[2:3]
	v_rcp_iflag_f32_e32 v2, v0
	v_cvt_f32_ubyte1_e32 v0, v195
	v_rcp_iflag_f32_e32 v3, v0
	v_cvt_f32_ubyte3_e32 v193, v190
	v_cvt_f32_ubyte2_e32 v192, v190
	v_pk_mul_f32 v[188:189], v[188:189], v[192:193]
	v_cvt_f32_ubyte2_e32 v0, v195
	v_pk_mul_f32 v[122:123], v[122:123], v[188:189]
	v_rcp_iflag_f32_e32 v188, v0
	v_cvt_f32_ubyte3_e32 v0, v195
	v_cvt_f32_ubyte1_e32 v195, v191
	v_cvt_f32_ubyte0_e32 v194, v191
	v_rcp_iflag_f32_e32 v189, v0
	v_pk_mul_f32 v[2:3], v[2:3], v[194:195]
	s_waitcnt vmcnt(12)
	v_mov_b32_e32 v219, v184
	v_mov_b32_e32 v220, v185
	v_mov_b32_e32 v221, v186
	v_mov_b32_e32 v222, v187
	v_cvt_f32_ubyte0_e32 v0, v184
	v_pk_mul_f32 v[116:117], v[116:117], v[2:3]
	v_rcp_iflag_f32_e32 v2, v0
	v_cvt_f32_ubyte1_e32 v0, v184
	v_rcp_iflag_f32_e32 v3, v0
	v_cvt_f32_ubyte3_e32 v193, v191
	v_cvt_f32_ubyte2_e32 v192, v191
	v_pk_mul_f32 v[188:189], v[188:189], v[192:193]
	v_cvt_f32_ubyte2_e32 v0, v184
	v_pk_mul_f32 v[118:119], v[118:119], v[188:189]
	v_rcp_iflag_f32_e32 v188, v0
	v_cvt_f32_ubyte3_e32 v0, v184
	v_cvt_f32_ubyte1_e32 v193, v180
	v_cvt_f32_ubyte0_e32 v192, v180
	v_rcp_iflag_f32_e32 v189, v0
	v_pk_mul_f32 v[2:3], v[2:3], v[192:193]
	v_cvt_f32_ubyte0_e32 v0, v185
	v_pk_mul_f32 v[112:113], v[112:113], v[2:3]
	v_rcp_iflag_f32_e32 v2, v0
	v_cvt_f32_ubyte1_e32 v0, v185
	v_rcp_iflag_f32_e32 v3, v0
	v_cvt_f32_ubyte3_e32 v191, v180
	v_cvt_f32_ubyte2_e32 v190, v180
	v_cvt_f32_ubyte2_e32 v0, v185
	v_pk_mul_f32 v[188:189], v[188:189], v[190:191]
	v_rcp_iflag_f32_e32 v184, v0
	v_cvt_f32_ubyte3_e32 v0, v185
	v_cvt_f32_ubyte1_e32 v191, v181
	v_cvt_f32_ubyte0_e32 v190, v181
	v_rcp_iflag_f32_e32 v185, v0
	v_pk_mul_f32 v[2:3], v[2:3], v[190:191]
	v_cvt_f32_ubyte0_e32 v0, v186
	v_pk_mul_f32 v[108:109], v[108:109], v[2:3]
	v_rcp_iflag_f32_e32 v2, v0
	v_cvt_f32_ubyte1_e32 v0, v186
	v_rcp_iflag_f32_e32 v3, v0
	v_pk_mul_f32 v[114:115], v[114:115], v[188:189]
	v_cvt_f32_ubyte3_e32 v189, v181
	v_cvt_f32_ubyte2_e32 v188, v181
	v_pk_mul_f32 v[180:181], v[184:185], v[188:189]
	v_cvt_f32_ubyte2_e32 v0, v186
	v_pk_mul_f32 v[110:111], v[110:111], v[180:181]
	v_rcp_iflag_f32_e32 v180, v0
	v_cvt_f32_ubyte3_e32 v0, v186
	v_cvt_f32_ubyte1_e32 v189, v182
	v_cvt_f32_ubyte0_e32 v188, v182
	v_rcp_iflag_f32_e32 v181, v0
	v_pk_mul_f32 v[2:3], v[2:3], v[188:189]
	v_cvt_f32_ubyte0_e32 v0, v187
	v_pk_mul_f32 v[104:105], v[104:105], v[2:3]
	v_rcp_iflag_f32_e32 v2, v0
	v_cvt_f32_ubyte1_e32 v0, v187
	v_rcp_iflag_f32_e32 v3, v0
	v_cvt_f32_ubyte3_e32 v185, v182
	v_cvt_f32_ubyte2_e32 v184, v182
	v_pk_mul_f32 v[180:181], v[180:181], v[184:185]
	v_cvt_f32_ubyte2_e32 v0, v187
	v_pk_mul_f32 v[106:107], v[106:107], v[180:181]
	v_rcp_iflag_f32_e32 v180, v0
	v_cvt_f32_ubyte3_e32 v0, v187
	v_cvt_f32_ubyte1_e32 v187, v183
	v_cvt_f32_ubyte0_e32 v186, v183
	v_rcp_iflag_f32_e32 v181, v0
	v_pk_mul_f32 v[2:3], v[2:3], v[186:187]
	s_waitcnt vmcnt(10)
; __device__ __forceinline__ float ub0(unsigned w) { return (float)(w & 0xffu); }
; __device__ __forceinline__ float ub1(unsigned w) { return (float)((w >> 8) & 0xffu); }
; __device__ __forceinline__ float ub2(unsigned w) { return (float)((w >> 16) & 0xffu); }
; __device__ __forceinline__ float ub3(unsigned w) { return (float)(w >> 24); }
; __device__ __forceinline__ void gate_ratio4(f32x4& v, unsigned n, unsigned d) {
;     v[0] *= ub0(n) * __builtin_amdgcn_rcpf(ub0(d)); v[1] *= ub1(n) * __builtin_amdgcn_rcpf(ub1(d)); v[2] *= ub2(n) * __builtin_amdgcn_rcpf(ub2(d)); v[3] *= ub3(n) * __builtin_amdgcn_rcpf(ub3(d)); }
;     __device__ __forceinline__ void mid(f32x4 (&acc)[2][2][4][2], const pg8::GUnit& u, int b, int wr, int wc, int fr, int fq) const {
;     ...
;         for (int k = 0; k < 8; ++k) { const int ai = k >> 2, m = k & 3;
;             gate_ratio4(acc[ai][0][m][0], gn[k].x, gd[k].x); gate_ratio4(acc[ai][0][m][1], gn[k].y, gd[k].y); gate_ratio4(acc[ai][1][m][0], gn[k].z, gd[k].z); gate_ratio4(acc[ai][1][m][1], gn[k].w, gd[k].w); }
	v_mov_b32_e32 v223, v176
	v_mov_b32_e32 v224, v177
	v_mov_b32_e32 v225, v178
	v_mov_b32_e32 v226, v179
	v_cvt_f32_ubyte0_e32 v0, v176
	v_pk_mul_f32 v[100:101], v[100:101], v[2:3]
	v_rcp_iflag_f32_e32 v2, v0
	v_cvt_f32_ubyte1_e32 v0, v176
	v_rcp_iflag_f32_e32 v3, v0
	v_cvt_f32_ubyte3_e32 v185, v183
	v_cvt_f32_ubyte2_e32 v184, v183
	v_pk_mul_f32 v[180:181], v[180:181], v[184:185]
	v_cvt_f32_ubyte2_e32 v0, v176
	v_pk_mul_f32 v[102:103], v[102:103], v[180:181]
	v_rcp_iflag_f32_e32 v180, v0
	v_cvt_f32_ubyte3_e32 v0, v176
	v_cvt_f32_ubyte1_e32 v185, v172
	v_cvt_f32_ubyte0_e32 v184, v172
	v_rcp_iflag_f32_e32 v181, v0
	v_pk_mul_f32 v[2:3], v[2:3], v[184:185]
	v_cvt_f32_ubyte0_e32 v0, v177
	v_pk_mul_f32 v[96:97], v[96:97], v[2:3]
	v_rcp_iflag_f32_e32 v2, v0
	v_cvt_f32_ubyte1_e32 v0, v177
	v_rcp_iflag_f32_e32 v3, v0
	v_cvt_f32_ubyte3_e32 v183, v172
	v_cvt_f32_ubyte2_e32 v182, v172
	v_cvt_f32_ubyte2_e32 v0, v177
	v_pk_mul_f32 v[180:181], v[180:181], v[182:183]
	v_rcp_iflag_f32_e32 v176, v0
	v_cvt_f32_ubyte3_e32 v0, v177
	v_cvt_f32_ubyte1_e32 v183, v173
	v_cvt_f32_ubyte0_e32 v182, v173
	v_rcp_iflag_f32_e32 v177, v0
	v_pk_mul_f32 v[2:3], v[2:3], v[182:183]
	v_cvt_f32_ubyte0_e32 v0, v178
	v_pk_mul_f32 v[92:93], v[92:93], v[2:3]
	v_rcp_iflag_f32_e32 v2, v0
	v_cvt_f32_ubyte1_e32 v0, v178
	v_rcp_iflag_f32_e32 v3, v0
	v_pk_mul_f32 v[98:99], v[98:99], v[180:181]
	v_cvt_f32_ubyte3_e32 v181, v173
	v_cvt_f32_ubyte2_e32 v180, v173
	v_pk_mul_f32 v[172:173], v[176:177], v[180:181]
	v_cvt_f32_ubyte2_e32 v0, v178
	v_pk_mul_f32 v[94:95], v[94:95], v[172:173]
	v_rcp_iflag_f32_e32 v172, v0
	v_cvt_f32_ubyte3_e32 v0, v178
	v_cvt_f32_ubyte1_e32 v181, v174
	v_cvt_f32_ubyte0_e32 v180, v174
	v_rcp_iflag_f32_e32 v173, v0
	v_pk_mul_f32 v[2:3], v[2:3], v[180:181]
	v_cvt_f32_ubyte0_e32 v0, v179
	v_pk_mul_f32 v[88:89], v[88:89], v[2:3]
	v_rcp_iflag_f32_e32 v2, v0
	v_cvt_f32_ubyte1_e32 v0, v179
	v_rcp_iflag_f32_e32 v3, v0
	v_cvt_f32_ubyte3_e32 v177, v174
	v_cvt_f32_ubyte2_e32 v176, v174
	v_pk_mul_f32 v[172:173], v[172:173], v[176:177]
	v_cvt_f32_ubyte2_e32 v0, v179
	v_pk_mul_f32 v[90:91], v[90:91], v[172:173]
	v_rcp_iflag_f32_e32 v172, v0
	v_cvt_f32_ubyte3_e32 v0, v179
	v_cvt_f32_ubyte1_e32 v179, v175
	v_cvt_f32_ubyte0_e32 v178, v175
	v_rcp_iflag_f32_e32 v173, v0
	v_pk_mul_f32 v[2:3], v[2:3], v[178:179]
	s_waitcnt vmcnt(8)
	v_mov_b32_e32 v227, v168
	v_mov_b32_e32 v228, v169
	v_mov_b32_e32 v229, v170
	v_mov_b32_e32 v230, v171
	v_cvt_f32_ubyte0_e32 v0, v168
	v_pk_mul_f32 v[84:85], v[84:85], v[2:3]
	v_rcp_iflag_f32_e32 v2, v0
	v_cvt_f32_ubyte1_e32 v0, v168
	v_rcp_iflag_f32_e32 v3, v0
	v_cvt_f32_ubyte3_e32 v177, v175
	v_cvt_f32_ubyte2_e32 v176, v175
	v_pk_mul_f32 v[172:173], v[172:173], v[176:177]
	v_cvt_f32_ubyte2_e32 v0, v168
	v_pk_mul_f32 v[86:87], v[86:87], v[172:173]
	v_rcp_iflag_f32_e32 v172, v0
	v_cvt_f32_ubyte3_e32 v0, v168
	v_cvt_f32_ubyte1_e32 v177, v164
	v_cvt_f32_ubyte0_e32 v176, v164
	v_rcp_iflag_f32_e32 v173, v0
	v_pk_mul_f32 v[2:3], v[2:3], v[176:177]
	v_cvt_f32_ubyte0_e32 v0, v169
	v_pk_mul_f32 v[80:81], v[80:81], v[2:3]
	v_rcp_iflag_f32_e32 v2, v0
	v_cvt_f32_ubyte1_e32 v0, v169
	v_rcp_iflag_f32_e32 v3, v0
	v_cvt_f32_ubyte3_e32 v175, v164
	v_cvt_f32_ubyte2_e32 v174, v164
	v_cvt_f32_ubyte2_e32 v0, v169
	v_pk_mul_f32 v[172:173], v[172:173], v[174:175]
	v_rcp_iflag_f32_e32 v168, v0
	v_cvt_f32_ubyte3_e32 v0, v169
	v_cvt_f32_ubyte1_e32 v175, v165
	v_cvt_f32_ubyte0_e32 v174, v165
	v_rcp_iflag_f32_e32 v169, v0
	v_pk_mul_f32 v[2:3], v[2:3], v[174:175]
	v_cvt_f32_ubyte0_e32 v0, v170
	v_pk_mul_f32 v[76:77], v[76:77], v[2:3]
	v_rcp_iflag_f32_e32 v2, v0
	v_cvt_f32_ubyte1_e32 v0, v170
	v_rcp_iflag_f32_e32 v3, v0
	v_pk_mul_f32 v[82:83], v[82:83], v[172:173]
	v_cvt_f32_ubyte3_e32 v173, v165
	v_cvt_f32_ubyte2_e32 v172, v165
	v_pk_mul_f32 v[164:165], v[168:169], v[172:173]
	v_cvt_f32_ubyte2_e32 v0, v170
	v_pk_mul_f32 v[78:79], v[78:79], v[164:165]
	v_rcp_iflag_f32_e32 v164, v0
	v_cvt_f32_ubyte3_e32 v0, v170
	v_cvt_f32_ubyte1_e32 v173, v166
	v_cvt_f32_ubyte0_e32 v172, v166
	v_rcp_iflag_f32_e32 v165, v0
	v_pk_mul_f32 v[2:3], v[2:3], v[172:173]
	v_cvt_f32_ubyte0_e32 v0, v171
	v_pk_mul_f32 v[72:73], v[72:73], v[2:3]
	v_rcp_iflag_f32_e32 v2, v0
	v_cvt_f32_ubyte1_e32 v0, v171
	v_rcp_iflag_f32_e32 v3, v0
	v_cvt_f32_ubyte3_e32 v169, v166
	v_cvt_f32_ubyte2_e32 v168, v166
	v_pk_mul_f32 v[164:165], v[164:165], v[168:169]
	v_cvt_f32_ubyte2_e32 v0, v171
	v_pk_mul_f32 v[74:75], v[74:75], v[164:165]
	v_rcp_iflag_f32_e32 v164, v0
	v_cvt_f32_ubyte3_e32 v0, v171
	v_cvt_f32_ubyte1_e32 v171, v167
	v_cvt_f32_ubyte0_e32 v170, v167
	v_rcp_iflag_f32_e32 v165, v0
	v_pk_mul_f32 v[2:3], v[2:3], v[170:171]
	s_waitcnt vmcnt(6)
; __device__ __forceinline__ float ub0(unsigned w) { return (float)(w & 0xffu); }
; __device__ __forceinline__ float ub1(unsigned w) { return (float)((w >> 8) & 0xffu); }
; __device__ __forceinline__ float ub2(unsigned w) { return (float)((w >> 16) & 0xffu); }
; __device__ __forceinline__ float ub3(unsigned w) { return (float)(w >> 24); }
; __device__ __forceinline__ void gate_ratio4(f32x4& v, unsigned n, unsigned d) {
;     v[0] *= ub0(n) * __builtin_amdgcn_rcpf(ub0(d)); v[1] *= ub1(n) * __builtin_amdgcn_rcpf(ub1(d)); v[2] *= ub2(n) * __builtin_amdgcn_rcpf(ub2(d)); v[3] *= ub3(n) * __builtin_amdgcn_rcpf(ub3(d)); }
;     __device__ __forceinline__ void mid(f32x4 (&acc)[2][2][4][2], const pg8::GUnit& u, int b, int wr, int wc, int fr, int fq) const {
;     ...
;         for (int k = 0; k < 8; ++k) { const int ai = k >> 2, m = k & 3;
;             gate_ratio4(acc[ai][0][m][0], gn[k].x, gd[k].x); gate_ratio4(acc[ai][0][m][1], gn[k].y, gd[k].y); gate_ratio4(acc[ai][1][m][0], gn[k].z, gd[k].z); gate_ratio4(acc[ai][1][m][1], gn[k].w, gd[k].w); }
	v_mov_b32_e32 v231, v160
	v_mov_b32_e32 v232, v161
	v_mov_b32_e32 v233, v162
	v_mov_b32_e32 v234, v163
	v_cvt_f32_ubyte0_e32 v0, v160
	v_pk_mul_f32 v[68:69], v[68:69], v[2:3]
	v_rcp_iflag_f32_e32 v2, v0
	v_cvt_f32_ubyte1_e32 v0, v160
	v_rcp_iflag_f32_e32 v3, v0
	v_cvt_f32_ubyte3_e32 v169, v167
	v_cvt_f32_ubyte2_e32 v168, v167
	v_pk_mul_f32 v[164:165], v[164:165], v[168:169]
	v_cvt_f32_ubyte2_e32 v0, v160
	v_pk_mul_f32 v[70:71], v[70:71], v[164:165]
	v_rcp_iflag_f32_e32 v164, v0
	v_cvt_f32_ubyte3_e32 v0, v160
	v_cvt_f32_ubyte1_e32 v169, v156
	v_cvt_f32_ubyte0_e32 v168, v156
	v_rcp_iflag_f32_e32 v165, v0
	v_pk_mul_f32 v[2:3], v[2:3], v[168:169]
	v_cvt_f32_ubyte0_e32 v0, v161
	v_pk_mul_f32 v[64:65], v[64:65], v[2:3]
	v_rcp_iflag_f32_e32 v2, v0
	v_cvt_f32_ubyte1_e32 v0, v161
	v_rcp_iflag_f32_e32 v3, v0
	v_cvt_f32_ubyte3_e32 v167, v156
	v_cvt_f32_ubyte2_e32 v166, v156
	v_cvt_f32_ubyte2_e32 v0, v161
	v_pk_mul_f32 v[164:165], v[164:165], v[166:167]
	v_rcp_iflag_f32_e32 v160, v0
	v_cvt_f32_ubyte3_e32 v0, v161
	v_cvt_f32_ubyte1_e32 v167, v157
	v_cvt_f32_ubyte0_e32 v166, v157
	v_rcp_iflag_f32_e32 v161, v0
	v_pk_mul_f32 v[2:3], v[2:3], v[166:167]
	v_cvt_f32_ubyte0_e32 v0, v162
	v_pk_mul_f32 v[60:61], v[60:61], v[2:3]
	v_rcp_iflag_f32_e32 v2, v0
	v_cvt_f32_ubyte1_e32 v0, v162
	v_rcp_iflag_f32_e32 v3, v0
	v_pk_mul_f32 v[66:67], v[66:67], v[164:165]
	v_cvt_f32_ubyte3_e32 v165, v157
	v_cvt_f32_ubyte2_e32 v164, v157
	v_pk_mul_f32 v[156:157], v[160:161], v[164:165]
	v_cvt_f32_ubyte2_e32 v0, v162
	v_pk_mul_f32 v[62:63], v[62:63], v[156:157]
	v_rcp_iflag_f32_e32 v156, v0
	v_cvt_f32_ubyte3_e32 v0, v162
	v_cvt_f32_ubyte1_e32 v165, v158
	v_cvt_f32_ubyte0_e32 v164, v158
	v_rcp_iflag_f32_e32 v157, v0
	v_pk_mul_f32 v[2:3], v[2:3], v[164:165]
	v_cvt_f32_ubyte0_e32 v0, v163
	v_pk_mul_f32 v[56:57], v[56:57], v[2:3]
	v_rcp_iflag_f32_e32 v2, v0
	v_cvt_f32_ubyte1_e32 v0, v163
	v_rcp_iflag_f32_e32 v3, v0
	v_cvt_f32_ubyte3_e32 v161, v158
	v_cvt_f32_ubyte2_e32 v160, v158
	v_pk_mul_f32 v[156:157], v[156:157], v[160:161]
	v_cvt_f32_ubyte2_e32 v0, v163
	v_pk_mul_f32 v[58:59], v[58:59], v[156:157]
	v_rcp_iflag_f32_e32 v156, v0
	v_cvt_f32_ubyte3_e32 v0, v163
	v_cvt_f32_ubyte1_e32 v163, v159
	v_cvt_f32_ubyte0_e32 v162, v159
	v_rcp_iflag_f32_e32 v157, v0
	v_pk_mul_f32 v[2:3], v[2:3], v[162:163]
	s_waitcnt vmcnt(4)
	v_mov_b32_e32 v235, v152
	v_mov_b32_e32 v236, v153
	v_mov_b32_e32 v237, v154
	v_mov_b32_e32 v238, v155
	v_cvt_f32_ubyte0_e32 v0, v152
	v_pk_mul_f32 v[52:53], v[52:53], v[2:3]
	v_rcp_iflag_f32_e32 v2, v0
	v_cvt_f32_ubyte1_e32 v0, v152
	v_rcp_iflag_f32_e32 v3, v0
	v_cvt_f32_ubyte3_e32 v161, v159
	v_cvt_f32_ubyte2_e32 v160, v159
	v_pk_mul_f32 v[156:157], v[156:157], v[160:161]
	v_cvt_f32_ubyte2_e32 v0, v152
	v_pk_mul_f32 v[54:55], v[54:55], v[156:157]
	v_rcp_iflag_f32_e32 v156, v0
	v_cvt_f32_ubyte3_e32 v0, v152
	v_cvt_f32_ubyte1_e32 v161, v148
	v_cvt_f32_ubyte0_e32 v160, v148
	v_rcp_iflag_f32_e32 v157, v0
	v_pk_mul_f32 v[2:3], v[2:3], v[160:161]
	v_cvt_f32_ubyte0_e32 v0, v153
	v_pk_mul_f32 v[48:49], v[48:49], v[2:3]
	v_rcp_iflag_f32_e32 v2, v0
	v_cvt_f32_ubyte1_e32 v0, v153
	v_rcp_iflag_f32_e32 v3, v0
	v_cvt_f32_ubyte3_e32 v159, v148
	v_cvt_f32_ubyte2_e32 v158, v148
	v_cvt_f32_ubyte2_e32 v0, v153
	v_pk_mul_f32 v[156:157], v[156:157], v[158:159]
	v_rcp_iflag_f32_e32 v152, v0
	v_cvt_f32_ubyte3_e32 v0, v153
	v_cvt_f32_ubyte1_e32 v159, v149
	v_cvt_f32_ubyte0_e32 v158, v149
	v_rcp_iflag_f32_e32 v153, v0
	v_pk_mul_f32 v[2:3], v[2:3], v[158:159]
	v_cvt_f32_ubyte0_e32 v0, v154
	v_pk_mul_f32 v[44:45], v[44:45], v[2:3]
	v_rcp_iflag_f32_e32 v2, v0
	v_cvt_f32_ubyte1_e32 v0, v154
	v_rcp_iflag_f32_e32 v3, v0
	v_pk_mul_f32 v[50:51], v[50:51], v[156:157]
	v_cvt_f32_ubyte3_e32 v157, v149
	v_cvt_f32_ubyte2_e32 v156, v149
	v_pk_mul_f32 v[148:149], v[152:153], v[156:157]
	v_cvt_f32_ubyte2_e32 v0, v154
	v_pk_mul_f32 v[46:47], v[46:47], v[148:149]
	v_rcp_iflag_f32_e32 v148, v0
	v_cvt_f32_ubyte3_e32 v0, v154
	v_cvt_f32_ubyte1_e32 v157, v150
	v_cvt_f32_ubyte0_e32 v156, v150
	v_rcp_iflag_f32_e32 v149, v0
	v_pk_mul_f32 v[2:3], v[2:3], v[156:157]
	v_cvt_f32_ubyte0_e32 v0, v155
	v_pk_mul_f32 v[40:41], v[40:41], v[2:3]
	v_rcp_iflag_f32_e32 v2, v0
	v_cvt_f32_ubyte1_e32 v0, v155
	v_rcp_iflag_f32_e32 v3, v0
	v_cvt_f32_ubyte3_e32 v153, v150
	v_cvt_f32_ubyte2_e32 v152, v150
	v_pk_mul_f32 v[148:149], v[148:149], v[152:153]
	v_cvt_f32_ubyte2_e32 v0, v155
	v_pk_mul_f32 v[42:43], v[42:43], v[148:149]
	v_rcp_iflag_f32_e32 v148, v0
	v_cvt_f32_ubyte3_e32 v0, v155
	v_cvt_f32_ubyte1_e32 v155, v151
	v_cvt_f32_ubyte0_e32 v154, v151
	v_rcp_iflag_f32_e32 v149, v0
	v_pk_mul_f32 v[2:3], v[2:3], v[154:155]
	s_waitcnt vmcnt(2)
; __device__ __forceinline__ float ub0(unsigned w) { return (float)(w & 0xffu); }
; __device__ __forceinline__ float ub1(unsigned w) { return (float)((w >> 8) & 0xffu); }
; __device__ __forceinline__ float ub2(unsigned w) { return (float)((w >> 16) & 0xffu); }
; __device__ __forceinline__ float ub3(unsigned w) { return (float)(w >> 24); }
; __device__ __forceinline__ void gate_ratio4(f32x4& v, unsigned n, unsigned d) {
;     v[0] *= ub0(n) * __builtin_amdgcn_rcpf(ub0(d)); v[1] *= ub1(n) * __builtin_amdgcn_rcpf(ub1(d)); v[2] *= ub2(n) * __builtin_amdgcn_rcpf(ub2(d)); v[3] *= ub3(n) * __builtin_amdgcn_rcpf(ub3(d)); }
;     __device__ __forceinline__ void mid(f32x4 (&acc)[2][2][4][2], const pg8::GUnit& u, int b, int wr, int wc, int fr, int fq) const {
;     ...
;         for (int k = 0; k < 8; ++k) { const int ai = k >> 2, m = k & 3;
;             gate_ratio4(acc[ai][0][m][0], gn[k].x, gd[k].x); gate_ratio4(acc[ai][0][m][1], gn[k].y, gd[k].y); gate_ratio4(acc[ai][1][m][0], gn[k].z, gd[k].z); gate_ratio4(acc[ai][1][m][1], gn[k].w, gd[k].w); }
	v_mov_b32_e32 v239, v144
	v_mov_b32_e32 v240, v145
	v_mov_b32_e32 v241, v146
	v_mov_b32_e32 v242, v147
	v_cvt_f32_ubyte0_e32 v0, v144
	v_pk_mul_f32 v[36:37], v[36:37], v[2:3]
	v_rcp_iflag_f32_e32 v2, v0
	v_cvt_f32_ubyte1_e32 v0, v144
	v_rcp_iflag_f32_e32 v3, v0
	v_cvt_f32_ubyte3_e32 v153, v151
	v_cvt_f32_ubyte2_e32 v152, v151
	v_pk_mul_f32 v[148:149], v[148:149], v[152:153]
	v_cvt_f32_ubyte2_e32 v0, v144
	v_pk_mul_f32 v[38:39], v[38:39], v[148:149]
	v_rcp_iflag_f32_e32 v148, v0
	v_cvt_f32_ubyte3_e32 v0, v144
	v_cvt_f32_ubyte1_e32 v153, v140
	v_cvt_f32_ubyte0_e32 v152, v140
	v_rcp_iflag_f32_e32 v149, v0
	v_pk_mul_f32 v[2:3], v[2:3], v[152:153]
	v_cvt_f32_ubyte0_e32 v0, v145
	v_pk_mul_f32 v[32:33], v[32:33], v[2:3]
	v_rcp_iflag_f32_e32 v2, v0
	v_cvt_f32_ubyte1_e32 v0, v145
	v_rcp_iflag_f32_e32 v3, v0
	v_cvt_f32_ubyte3_e32 v151, v140
	v_cvt_f32_ubyte2_e32 v150, v140
	v_cvt_f32_ubyte2_e32 v0, v145
	v_pk_mul_f32 v[148:149], v[148:149], v[150:151]
	v_rcp_iflag_f32_e32 v144, v0
	v_cvt_f32_ubyte3_e32 v0, v145
	v_cvt_f32_ubyte1_e32 v151, v141
	v_cvt_f32_ubyte0_e32 v150, v141
	v_rcp_iflag_f32_e32 v145, v0
	v_pk_mul_f32 v[2:3], v[2:3], v[150:151]
	v_cvt_f32_ubyte0_e32 v0, v146
	v_pk_mul_f32 v[28:29], v[28:29], v[2:3]
	v_rcp_iflag_f32_e32 v2, v0
	v_cvt_f32_ubyte1_e32 v0, v146
	v_rcp_iflag_f32_e32 v3, v0
	v_pk_mul_f32 v[34:35], v[34:35], v[148:149]
	v_cvt_f32_ubyte3_e32 v149, v141
	v_cvt_f32_ubyte2_e32 v148, v141
	v_pk_mul_f32 v[140:141], v[144:145], v[148:149]
	v_cvt_f32_ubyte2_e32 v0, v146
	v_pk_mul_f32 v[30:31], v[30:31], v[140:141]
	v_rcp_iflag_f32_e32 v140, v0
	v_cvt_f32_ubyte3_e32 v0, v146
	v_cvt_f32_ubyte1_e32 v149, v142
	v_cvt_f32_ubyte0_e32 v148, v142
	v_rcp_iflag_f32_e32 v141, v0
	v_pk_mul_f32 v[2:3], v[2:3], v[148:149]
	v_cvt_f32_ubyte0_e32 v0, v147
	v_pk_mul_f32 v[24:25], v[24:25], v[2:3]
	v_rcp_iflag_f32_e32 v2, v0
	v_cvt_f32_ubyte1_e32 v0, v147
	v_rcp_iflag_f32_e32 v3, v0
	v_cvt_f32_ubyte3_e32 v145, v142
	v_cvt_f32_ubyte2_e32 v144, v142
	v_pk_mul_f32 v[140:141], v[140:141], v[144:145]
	v_cvt_f32_ubyte2_e32 v0, v147
	v_pk_mul_f32 v[26:27], v[26:27], v[140:141]
	v_rcp_iflag_f32_e32 v140, v0
	v_cvt_f32_ubyte3_e32 v0, v147
	v_cvt_f32_ubyte1_e32 v147, v143
	v_cvt_f32_ubyte0_e32 v146, v143
	v_rcp_iflag_f32_e32 v141, v0
	v_pk_mul_f32 v[2:3], v[2:3], v[146:147]
	s_waitcnt vmcnt(0)
	v_mov_b32_e32 v243, v136
	v_mov_b32_e32 v245, v137
	v_mov_b32_e32 v246, v138
	v_mov_b32_e32 v247, v139
	v_cvt_f32_ubyte0_e32 v0, v136
	v_pk_mul_f32 v[20:21], v[20:21], v[2:3]
	v_rcp_iflag_f32_e32 v2, v0
	v_cvt_f32_ubyte1_e32 v0, v136
	v_rcp_iflag_f32_e32 v3, v0
	v_cvt_f32_ubyte3_e32 v145, v143
	v_cvt_f32_ubyte2_e32 v144, v143
	v_pk_mul_f32 v[140:141], v[140:141], v[144:145]
	v_cvt_f32_ubyte2_e32 v0, v136
	v_pk_mul_f32 v[22:23], v[22:23], v[140:141]
	v_rcp_iflag_f32_e32 v140, v0
	v_cvt_f32_ubyte3_e32 v0, v136
	v_cvt_f32_ubyte1_e32 v145, v132
	v_cvt_f32_ubyte0_e32 v144, v132
	v_rcp_iflag_f32_e32 v141, v0
	v_pk_mul_f32 v[2:3], v[2:3], v[144:145]
	v_cvt_f32_ubyte0_e32 v0, v137
	v_pk_mul_f32 v[16:17], v[16:17], v[2:3]
	v_rcp_iflag_f32_e32 v2, v0
	v_cvt_f32_ubyte1_e32 v0, v137
	v_rcp_iflag_f32_e32 v3, v0
	v_cvt_f32_ubyte2_e32 v0, v137
	v_rcp_iflag_f32_e32 v136, v0
	v_cvt_f32_ubyte3_e32 v0, v137
	v_cvt_f32_ubyte3_e32 v143, v132
	v_cvt_f32_ubyte2_e32 v142, v132
	v_rcp_iflag_f32_e32 v137, v0
	v_pk_mul_f32 v[140:141], v[140:141], v[142:143]
	v_cvt_f32_ubyte1_e32 v143, v133
	v_cvt_f32_ubyte0_e32 v142, v133
	v_pk_mul_f32 v[2:3], v[2:3], v[142:143]
	v_cvt_f32_ubyte0_e32 v0, v138
	v_pk_mul_f32 v[18:19], v[18:19], v[140:141]
	v_cvt_f32_ubyte3_e32 v141, v133
	v_cvt_f32_ubyte2_e32 v140, v133
	v_pk_mul_f32 v[12:13], v[12:13], v[2:3]
	v_rcp_iflag_f32_e32 v2, v0
	v_cvt_f32_ubyte1_e32 v0, v138
	v_pk_mul_f32 v[132:133], v[136:137], v[140:141]
	v_rcp_iflag_f32_e32 v3, v0
	v_cvt_f32_ubyte2_e32 v0, v138
	v_pk_mul_f32 v[14:15], v[14:15], v[132:133]
	v_rcp_iflag_f32_e32 v132, v0
	v_cvt_f32_ubyte3_e32 v0, v138
	v_rcp_iflag_f32_e32 v133, v0
	v_cvt_f32_ubyte1_e32 v141, v134
	v_cvt_f32_ubyte0_e32 v140, v134
	v_pk_mul_f32 v[2:3], v[2:3], v[140:141]
	v_cvt_f32_ubyte0_e32 v0, v139
	v_cvt_f32_ubyte3_e32 v137, v134
	v_cvt_f32_ubyte2_e32 v136, v134
	v_pk_mul_f32 v[8:9], v[8:9], v[2:3]
	v_rcp_iflag_f32_e32 v2, v0
	v_cvt_f32_ubyte1_e32 v0, v139
	v_pk_mul_f32 v[132:133], v[132:133], v[136:137]
	v_rcp_iflag_f32_e32 v3, v0
	v_cvt_f32_ubyte2_e32 v0, v139
	v_pk_mul_f32 v[10:11], v[10:11], v[132:133]
	v_rcp_iflag_f32_e32 v132, v0
	v_cvt_f32_ubyte3_e32 v0, v139
	v_rcp_iflag_f32_e32 v133, v0
	v_cvt_f32_ubyte3_e32 v137, v135
	v_cvt_f32_ubyte2_e32 v136, v135
	v_cvt_f32_ubyte1_e32 v139, v135
	v_cvt_f32_ubyte0_e32 v138, v135
	v_pk_mul_f32 v[2:3], v[2:3], v[138:139]
	v_pk_mul_f32 v[132:133], v[132:133], v[136:137]
	v_pk_mul_f32 v[4:5], v[4:5], v[2:3]
	v_pk_mul_f32 v[6:7], v[6:7], v[132:133]
